# stick-breaking tile math rewritten: diagonal tile peeled (only it applies masks), within-tile suffix sums exchanged between half-waves with permlane32 swaps instead of LDS bpermute, fewer VALU ops
# speedup vs baseline: 1.0010x; 1.0010x over previous
; __device__ __forceinline__ int crow(int r, int hi) { return (r & 3) + 8 * (r >> 2) + 4 * hi; }
; template <bool DRY> __device__ __forceinline__ void sb_unit(int b, int h, int qi, bf16_t* Pm, const bf16_t* VT) {
;     ...
;         sb_load(nxt, Pm, VT, tok0, (kt > 0 ? kt - 1 : 0) * 32, h, r32, hi);
;         f32x16 p = {};
; #pragma unroll
;         for (int s = 0; s < 4; ++s) p = __builtin_amdgcn_mfma_f32_32x32x16_bf16(cur.kf[s], qf[s], p, 0, 0, 0);
;         const bool diag = (kt == qi);
;         float lk[16], inner[16], Tg[4], TP[4], pre[4];
; #pragma unroll
;         for (int r = 0; r < 16; ++r) {
;             const float z = p[r] * 0.125f; p[r] = z;
;             const float e = __expf(-fabsf(z)); const float sp = fmaxf(z, 0.f) + __logf(1.f + e);
;             const bool valid = !diag || (crow(r, hi) < r32);
;             lk[r] = valid ? -sp : 0.f;
;         }
; #pragma unroll
;         for (int g = 0; g < 4; ++g) {
;             const float s3 = lk[4 * g + 3], s2 = s3 + lk[4 * g + 2], s1 = s2 + lk[4 * g + 1];
;             inner[4 * g + 3] = 0.f; inner[4 * g + 2] = s3; inner[4 * g + 1] = s2; inner[4 * g] = s1; Tg[g] = s1 + lk[4 * g];
;             TP[g] = __shfl_xor(Tg[g], 32);
.LBB0_742:
	v_med3_i32 v36, v100, 0, 1
	v_lshlrev_b32_e32 v36, 5, v36
	s_mov_b32 s4, 0x208000
	v_sub_u32_e32 v40, v99, v36
	v_add_co_u32_e32 v36, vcc, s4, v94
	v_mov_b32_e32 v41, v2
	s_nop 0
	v_addc_co_u32_e32 v37, vcc, 0, v95, vcc
	global_load_dwordx4 v[156:159], v[36:37], off offset:32
	global_load_dwordx4 v[160:163], v[94:95], off offset:32
	global_load_dwordx4 v[164:167], v[36:37], off
	global_load_dwordx4 v[168:171], v[94:95], off
	v_mad_u64_u32 v[36:37], s[4:5], v90, s24, v[92:93]
	v_mov_b32_e32 v38, v37
	v_mad_u64_u32 v[38:39], s[4:5], v91, s24, v[38:39]
	v_mov_b32_e32 v37, v38
	global_load_dwordx4 v[152:155], v[36:37], off offset:2400
	global_load_dwordx4 v[148:151], v[36:37], off offset:2368
	global_load_dwordx4 v[144:147], v[36:37], off offset:2336
	s_nop 0
	global_load_dwordx4 v[140:143], v[36:37], off offset:2304
	v_lshl_add_u64 v[90:91], v[0:1], 0, v[40:41]
	v_lshl_add_u64 v[94:95], v[40:41], 1, v[88:89]
	v_add_u32_e32 v100, -1, v100
	v_subrev_u32_e32 v99, 32, v99
	s_waitcnt vmcnt(8)
	v_mfma_f32_32x32x16_bf16 v[36:51], v[172:175], v[52:55], 0
	v_mfma_f32_32x32x16_bf16 v[36:51], v[176:179], v[56:59], v[36:51]
	v_mfma_f32_32x32x16_bf16 v[36:51], v[180:183], v[60:63], v[36:51]
	v_mfma_f32_32x32x16_bf16 v[36:51], v[184:187], v[64:67], v[36:51]
	v_permlane32_swap_b32_e32 v80, v82
	v_permlane32_swap_b32_e32 v81, v83
	v_permlane32_swap_b32_e32 v72, v74
	v_permlane32_swap_b32_e32 v73, v75
	v_permlane32_swap_b32_e32 v76, v78
	v_permlane32_swap_b32_e32 v77, v79
	v_permlane32_swap_b32_e32 v68, v70
	v_permlane32_swap_b32_e32 v69, v71
	s_nop 3
	v_mul_f32_e32 v36, 0x3e38aa3b, v36
	v_mul_f32_e32 v37, 0x3e38aa3b, v37
	v_exp_f32_e64 v96, -|v36|
	v_exp_f32_e64 v97, -|v37|
	v_min_f32_e64 v104, -v36, 0
	v_min_f32_e64 v105, -v37, 0
	v_add_f32_e32 v96, 1.0, v96
	v_add_f32_e32 v97, 1.0, v97
	v_log_f32_e32 v96, v96
	v_log_f32_e32 v97, v97
	v_cndmask_b32_e64 v121, v102, 0, s[12:13]
	v_sub_f32_e32 v104, v104, v96
	v_sub_f32_e32 v105, v105, v97
	v_cndmask_b32_e64 v104, 0, v104, s[44:45]
	v_cndmask_b32_e64 v105, 0, v105, s[46:47]
	v_mul_f32_e32 v38, 0x3e38aa3b, v38
	v_mul_f32_e32 v39, 0x3e38aa3b, v39
	v_exp_f32_e64 v103, -|v38|
	v_exp_f32_e64 v120, -|v39|
	v_min_f32_e64 v106, -v38, 0
	v_min_f32_e64 v107, -v39, 0
	v_add_f32_e32 v103, 1.0, v103
	v_add_f32_e32 v120, 1.0, v120
	v_log_f32_e32 v103, v103
	v_log_f32_e32 v120, v120
	v_sub_f32_e32 v106, v106, v103
	v_sub_f32_e32 v107, v107, v120
	v_cndmask_b32_e64 v106, 0, v106, s[48:49]
	v_cndmask_b32_e64 v107, 0, v107, s[50:51]
	v_mul_f32_e32 v40, 0x3e38aa3b, v40
	v_mul_f32_e32 v41, 0x3e38aa3b, v41
	v_exp_f32_e64 v96, -|v40|
	v_exp_f32_e64 v97, -|v41|
	v_min_f32_e64 v108, -v40, 0
	v_min_f32_e64 v109, -v41, 0
	v_add_f32_e32 v96, 1.0, v96
	v_add_f32_e32 v97, 1.0, v97
	v_log_f32_e32 v96, v96
	v_log_f32_e32 v97, v97
	v_sub_f32_e32 v108, v108, v96
	v_sub_f32_e32 v109, v109, v97
	v_cndmask_b32_e64 v108, 0, v108, s[52:53]
	v_cndmask_b32_e64 v109, 0, v109, s[54:55]
	v_mul_f32_e32 v42, 0x3e38aa3b, v42
	v_mul_f32_e32 v43, 0x3e38aa3b, v43
	v_exp_f32_e64 v103, -|v42|
	v_exp_f32_e64 v120, -|v43|
	v_min_f32_e64 v110, -v42, 0
	v_min_f32_e64 v111, -v43, 0
	v_add_f32_e32 v103, 1.0, v103
	v_add_f32_e32 v120, 1.0, v120
	v_log_f32_e32 v103, v103
	v_log_f32_e32 v120, v120
	v_sub_f32_e32 v110, v110, v103
	v_sub_f32_e32 v111, v111, v120
	v_cndmask_b32_e64 v110, 0, v110, s[56:57]
	v_cndmask_b32_e64 v111, 0, v111, s[58:59]
	v_mul_f32_e32 v44, 0x3e38aa3b, v44
	v_mul_f32_e32 v45, 0x3e38aa3b, v45
	v_exp_f32_e64 v96, -|v44|
	v_exp_f32_e64 v97, -|v45|
	v_min_f32_e64 v112, -v44, 0
	v_min_f32_e64 v113, -v45, 0
	v_add_f32_e32 v96, 1.0, v96
	v_add_f32_e32 v97, 1.0, v97
	v_log_f32_e32 v96, v96
	v_log_f32_e32 v97, v97
	v_sub_f32_e32 v112, v112, v96
	v_sub_f32_e32 v113, v113, v97
	v_cndmask_b32_e64 v112, 0, v112, s[60:61]
	v_cndmask_b32_e64 v113, 0, v113, s[62:63]
	v_mul_f32_e32 v46, 0x3e38aa3b, v46
	v_mul_f32_e32 v47, 0x3e38aa3b, v47
	v_exp_f32_e64 v103, -|v46|
	v_exp_f32_e64 v120, -|v47|
	v_min_f32_e64 v114, -v46, 0
	v_min_f32_e64 v115, -v47, 0
	v_add_f32_e32 v103, 1.0, v103
	v_add_f32_e32 v120, 1.0, v120
	v_log_f32_e32 v103, v103
	v_log_f32_e32 v120, v120
	v_sub_f32_e32 v114, v114, v103
	v_sub_f32_e32 v115, v115, v120
	v_cndmask_b32_e64 v114, 0, v114, s[64:65]
	v_cndmask_b32_e64 v115, 0, v115, s[66:67]
	v_mul_f32_e32 v48, 0x3e38aa3b, v48
	v_mul_f32_e32 v49, 0x3e38aa3b, v49
	v_exp_f32_e64 v96, -|v48|
	v_exp_f32_e64 v97, -|v49|
	v_min_f32_e64 v116, -v48, 0
	v_min_f32_e64 v117, -v49, 0
	v_add_f32_e32 v96, 1.0, v96
	v_add_f32_e32 v97, 1.0, v97
	v_log_f32_e32 v96, v96
	v_log_f32_e32 v97, v97
	v_sub_f32_e32 v116, v116, v96
	v_sub_f32_e32 v117, v117, v97
	v_cndmask_b32_e64 v116, 0, v116, s[68:69]
	v_cndmask_b32_e64 v117, 0, v117, s[70:71]
	v_mul_f32_e32 v50, 0x3e38aa3b, v50
	v_mul_f32_e32 v51, 0x3e38aa3b, v51
	v_exp_f32_e64 v103, -|v50|
	v_exp_f32_e64 v120, -|v51|
	v_min_f32_e64 v118, -v50, 0
	v_min_f32_e64 v119, -v51, 0
	v_add_f32_e32 v103, 1.0, v103
	v_add_f32_e32 v120, 1.0, v120
	v_log_f32_e32 v103, v103
	v_log_f32_e32 v120, v120
	v_sub_f32_e32 v118, v118, v103
	v_sub_f32_e32 v119, v119, v120
	v_cndmask_b32_e64 v118, 0, v118, s[72:73]
	v_cndmask_b32_e64 v119, 0, v119, s[74:75]
	v_add_f32_e32 v106, v106, v107
	v_add_f32_e32 v110, v110, v111
	v_add_f32_e32 v114, v114, v115
	v_add_f32_e32 v118, v118, v119
	v_add_f32_e32 v105, v105, v106
	v_add_f32_e32 v109, v109, v110
	v_add_f32_e32 v113, v113, v114
	v_add_f32_e32 v117, v117, v118
	v_add_f32_e32 v104, v104, v105
	v_add_f32_e32 v108, v108, v109
	v_add_f32_e32 v112, v112, v113
	v_add_f32_e32 v116, v116, v117
	v_add_f32_e32 v122, v116, v121
	v_add_f32_e32 v36, v36, v104
	v_add_f32_e32 v37, v37, v105
; __device__ __forceinline__ unsigned cvtpk(float lo, float hi) { f32x2_t v = {lo, hi}; bf16x2_t b = __builtin_convertvector(v, bf16x2_t); return __builtin_bit_cast(unsigned, b); }
; __device__ __forceinline__ int crow(int r, int hi) { return (r & 3) + 8 * (r >> 2) + 4 * hi; }
; template <bool DRY> __device__ __forceinline__ void sb_unit(int b, int h, int qi, bf16_t* Pm, const bf16_t* VT) {
;     ...
;             TP[g] = __shfl_xor(Tg[g], 32);
;         }
;         float run = 0.f;
; #pragma unroll
;         for (int g = 3; g >= 0; --g) { pre[g] = run + (hi == 0 ? TP[g] : 0.f); run += Tg[g] + TP[g]; }
; #pragma unroll
;         for (int r = 0; r < 16; ++r) {
;             const bool valid = !diag || (crow(r, hi) < r32);
;             const float ex = fminf(p[r] + lk[r] + R + pre[r >> 2] + inner[r], 0.f);
;             p[r] = valid ? __expf(ex) : 0.f;
;         }
;         R += run;
; #pragma unroll
;         for (int s = 0; s < 2; ++s) {
;             const u32x4 pw = (u32x4){cvtpk(p[8 * s + 0], p[8 * s + 1]), cvtpk(p[8 * s + 2], p[8 * s + 3]), cvtpk(p[8 * s + 4], p[8 * s + 5]), cvtpk(p[8 * s + 6], p[8 * s + 7])};
;             const bf16x8 pf = __builtin_bit_cast(bf16x8, pw);
;             const s16x4 l0 = cur.v[4 * s], h0 = cur.v[4 * s + 1], l1 = cur.v[4 * s + 2], h1 = cur.v[4 * s + 3];
;             const bf16x8 v0 = (bf16x8){l0[0], l0[1], l0[2], l0[3], h0[0], h0[1], h0[2], h0[3]};
;             const bf16x8 v1 = (bf16x8){l1[0], l1[1], l1[2], l1[3], h1[0], h1[1], h1[2], h1[3]};
;             o0 = __builtin_amdgcn_mfma_f32_32x32x16_bf16(v0, pf, o0, 0, 0, 0);
;             o1 = __builtin_amdgcn_mfma_f32_32x32x16_bf16(v1, pf, o1, 0, 0, 0);
;         }
;         if (__all(R < -104.f)) break;
;         cur = nxt;
;     }
	v_add_f32_e32 v38, v38, v106
	v_add_f32_e32 v39, v39, v107
	v_add_f32_e32 v123, v122, v112
	v_add_f32_e32 v40, v40, v108
	v_add_f32_e32 v41, v41, v109
	v_add_f32_e32 v42, v42, v110
	v_add_f32_e32 v43, v43, v111
	v_add_f32_e32 v124, v123, v108
	v_add_f32_e32 v44, v44, v112
	v_add_f32_e32 v45, v45, v113
	v_add_f32_e32 v46, v46, v114
	v_add_f32_e32 v47, v47, v115
	v_add_f32_e32 v125, v124, v104
	v_add_f32_e32 v48, v48, v116
	v_add_f32_e32 v49, v49, v117
	v_add_f32_e32 v50, v50, v118
	v_add_f32_e32 v51, v51, v119
	v_mov_b32_e32 v126, v122
	v_cndmask_b32_e64 v130, v121, v125, s[12:13]
	v_cndmask_b32_e64 v127, v123, v122, s[12:13]
	v_cndmask_b32_e64 v128, v124, v123, s[12:13]
	v_cndmask_b32_e64 v129, v125, v124, s[12:13]
	v_permlane32_swap_b32_e32 v126, v130
	v_permlane32_swap_b32_e32 v127, v122
	v_permlane32_swap_b32_e32 v128, v123
	v_permlane32_swap_b32_e32 v129, v124
	v_add_f32_e32 v102, v125, v126
	v_add_f32_e32 v127, v127, v122
	v_add_f32_e32 v128, v128, v123
	v_add_f32_e32 v129, v129, v124
	v_add_f32_e32 v48, v48, v130
	v_add_f32_e32 v49, v49, v130
	v_add_f32_e32 v50, v50, v130
	v_add_f32_e32 v51, v51, v130
	v_add_f32_e32 v44, v44, v127
	v_add_f32_e32 v45, v45, v127
	v_add_f32_e32 v46, v46, v127
	v_add_f32_e32 v47, v47, v127
	v_add_f32_e32 v40, v40, v128
	v_add_f32_e32 v41, v41, v128
	v_add_f32_e32 v42, v42, v128
	v_add_f32_e32 v43, v43, v128
	v_add_f32_e32 v36, v36, v129
	v_add_f32_e32 v37, v37, v129
	v_add_f32_e32 v38, v38, v129
	v_add_f32_e32 v39, v39, v129
	v_exp_f32_e64 v36, v36 clamp
	v_exp_f32_e64 v37, v37 clamp
	v_exp_f32_e64 v38, v38 clamp
	v_exp_f32_e64 v39, v39 clamp
	v_exp_f32_e64 v40, v40 clamp
	v_exp_f32_e64 v41, v41 clamp
	v_exp_f32_e64 v42, v42 clamp
	v_exp_f32_e64 v43, v43 clamp
	v_exp_f32_e64 v44, v44 clamp
	v_exp_f32_e64 v45, v45 clamp
	v_exp_f32_e64 v46, v46 clamp
	v_exp_f32_e64 v47, v47 clamp
	v_exp_f32_e64 v48, v48 clamp
	v_exp_f32_e64 v49, v49 clamp
	v_exp_f32_e64 v50, v50 clamp
	v_exp_f32_e64 v51, v51 clamp
	s_nop 0
	v_cndmask_b32_e64 v36, 0, v36, s[44:45]
	v_cndmask_b32_e64 v37, 0, v37, s[46:47]
	v_cndmask_b32_e64 v38, 0, v38, s[48:49]
	v_cndmask_b32_e64 v39, 0, v39, s[50:51]
	v_cndmask_b32_e64 v40, 0, v40, s[52:53]
	v_cndmask_b32_e64 v41, 0, v41, s[54:55]
	v_cndmask_b32_e64 v42, 0, v42, s[56:57]
	v_cndmask_b32_e64 v43, 0, v43, s[58:59]
	v_cndmask_b32_e64 v44, 0, v44, s[60:61]
	v_cndmask_b32_e64 v45, 0, v45, s[62:63]
	v_cndmask_b32_e64 v46, 0, v46, s[64:65]
	v_cndmask_b32_e64 v47, 0, v47, s[66:67]
	v_cndmask_b32_e64 v48, 0, v48, s[68:69]
	v_cndmask_b32_e64 v49, 0, v49, s[70:71]
	v_cndmask_b32_e64 v50, 0, v50, s[72:73]
	v_cndmask_b32_e64 v51, 0, v51, s[74:75]
	v_cvt_pk_bf16_f32 v36, v36, v37
	v_cvt_pk_bf16_f32 v37, v38, v39
	v_cvt_pk_bf16_f32 v38, v40, v41
	v_cvt_pk_bf16_f32 v39, v42, v43
	s_mov_b32 s4, 0xc3160a50
	v_cmp_gt_f32_e32 vcc, s4, v102
	v_mfma_f32_32x32x16_bf16 v[4:19], v[80:83], v[36:39], v[4:19]
	v_cvt_pk_bf16_f32 v44, v44, v45
	v_cvt_pk_bf16_f32 v45, v46, v47
	v_mfma_f32_32x32x16_bf16 v[20:35], v[76:79], v[36:39], v[20:35]
	v_cvt_pk_bf16_f32 v46, v48, v49
	v_cvt_pk_bf16_f32 v47, v50, v51
	s_cmp_eq_u32 vcc_hi, exec_hi
	s_cselect_b64 s[4:5], -1, 0
	v_cmp_eq_u32_e32 vcc, s28, v98
	s_or_b64 s[4:5], s[4:5], vcc
	s_add_i32 s28, s28, 1
	s_and_b64 s[4:5], exec, s[4:5]
	s_or_b64 s[34:35], s[4:5], s[34:35]
	v_mfma_f32_32x32x16_bf16 v[4:19], v[72:75], v[44:47], v[4:19]
	v_mfma_f32_32x32x16_bf16 v[20:35], v[68:71], v[44:47], v[20:35]
	s_andn2_b64 exec, exec, s[34:35]
	s_cbranch_execz .Lsbu_exit
.Lsbu_loop:
	v_med3_i32 v36, v100, 0, 1
	v_lshlrev_b32_e32 v36, 5, v36
	s_mov_b32 s4, 0x208000
	v_sub_u32_e32 v40, v99, v36
	v_add_co_u32_e32 v36, vcc, s4, v94
	v_mov_b32_e32 v41, v2
	s_nop 0
	v_addc_co_u32_e32 v37, vcc, 0, v95, vcc
	global_load_dwordx4 v[68:71], v[36:37], off offset:32
	global_load_dwordx4 v[72:75], v[94:95], off offset:32
	global_load_dwordx4 v[76:79], v[36:37], off
	global_load_dwordx4 v[80:83], v[94:95], off
	v_mad_u64_u32 v[36:37], s[4:5], v90, s24, v[92:93]
	v_mov_b32_e32 v38, v37
	v_mad_u64_u32 v[38:39], s[4:5], v91, s24, v[38:39]
	v_mov_b32_e32 v37, v38
	global_load_dwordx4 v[184:187], v[36:37], off offset:2400
	global_load_dwordx4 v[180:183], v[36:37], off offset:2368
	global_load_dwordx4 v[176:179], v[36:37], off offset:2336
	s_nop 0
	global_load_dwordx4 v[172:175], v[36:37], off offset:2304
	v_lshl_add_u64 v[90:91], v[0:1], 0, v[40:41]
	v_lshl_add_u64 v[94:95], v[40:41], 1, v[88:89]
	v_add_u32_e32 v100, -1, v100
	v_subrev_u32_e32 v99, 32, v99
	s_waitcnt vmcnt(8)
; __device__ __forceinline__ int crow(int r, int hi) { return (r & 3) + 8 * (r >> 2) + 4 * hi; }
; template <bool DRY> __device__ __forceinline__ void sb_unit(int b, int h, int qi, bf16_t* Pm, const bf16_t* VT) {
;     ...
;         for (int s = 0; s < 4; ++s) p = __builtin_amdgcn_mfma_f32_32x32x16_bf16(cur.kf[s], qf[s], p, 0, 0, 0);
;         const bool diag = (kt == qi);
;         float lk[16], inner[16], Tg[4], TP[4], pre[4];
; #pragma unroll
;         for (int r = 0; r < 16; ++r) {
;             const float z = p[r] * 0.125f; p[r] = z;
;             const float e = __expf(-fabsf(z)); const float sp = fmaxf(z, 0.f) + __logf(1.f + e);
;             const bool valid = !diag || (crow(r, hi) < r32);
;             lk[r] = valid ? -sp : 0.f;
;         }
; #pragma unroll
;         for (int g = 0; g < 4; ++g) {
;             const float s3 = lk[4 * g + 3], s2 = s3 + lk[4 * g + 2], s1 = s2 + lk[4 * g + 1];
;             inner[4 * g + 3] = 0.f; inner[4 * g + 2] = s3; inner[4 * g + 1] = s2; inner[4 * g] = s1; Tg[g] = s1 + lk[4 * g];
;             TP[g] = __shfl_xor(Tg[g], 32);
;         }
;         float run = 0.f;
; #pragma unroll
;         for (int g = 3; g >= 0; --g) { pre[g] = run + (hi == 0 ? TP[g] : 0.f); run += Tg[g] + TP[g]; }
; #pragma unroll
;         for (int r = 0; r < 16; ++r) {
;             const bool valid = !diag || (crow(r, hi) < r32);
;             const float ex = fminf(p[r] + lk[r] + R + pre[r >> 2] + inner[r], 0.f);
;             p[r] = valid ? __expf(ex) : 0.f;
;         }
;         R += run;
; #pragma unroll
;         for (int s = 0; s < 2; ++s) {
;             const u32x4 pw = (u32x4){cvtpk(p[8 * s + 0], p[8 * s + 1]), cvtpk(p[8 * s + 2], p[8 * s + 3]), cvtpk(p[8 * s + 4], p[8 * s + 5]), cvtpk(p[8 * s + 6], p[8 * s + 7])};
;             const bf16x8 pf = __builtin_bit_cast(bf16x8, pw);
;             const s16x4 l0 = cur.v[4 * s], h0 = cur.v[4 * s + 1], l1 = cur.v[4 * s + 2], h1 = cur.v[4 * s + 3];
;             const bf16x8 v0 = (bf16x8){l0[0], l0[1], l0[2], l0[3], h0[0], h0[1], h0[2], h0[3]};
;             const bf16x8 v1 = (bf16x8){l1[0], l1[1], l1[2], l1[3], h1[0], h1[1], h1[2], h1[3]};
;             o0 = __builtin_amdgcn_mfma_f32_32x32x16_bf16(v0, pf, o0, 0, 0, 0);
;             o1 = __builtin_amdgcn_mfma_f32_32x32x16_bf16(v1, pf, o1, 0, 0, 0);
;         }
;         if (__all(R < -104.f)) break;
	v_mfma_f32_32x32x16_bf16 v[36:51], v[140:143], v[52:55], 0
	v_mfma_f32_32x32x16_bf16 v[36:51], v[144:147], v[56:59], v[36:51]
	v_mfma_f32_32x32x16_bf16 v[36:51], v[148:151], v[60:63], v[36:51]
	v_mfma_f32_32x32x16_bf16 v[36:51], v[152:155], v[64:67], v[36:51]
	v_permlane32_swap_b32_e32 v168, v170
	v_permlane32_swap_b32_e32 v169, v171
	v_permlane32_swap_b32_e32 v160, v162
	v_permlane32_swap_b32_e32 v161, v163
	v_permlane32_swap_b32_e32 v164, v166
	v_permlane32_swap_b32_e32 v165, v167
	v_permlane32_swap_b32_e32 v156, v158
	v_permlane32_swap_b32_e32 v157, v159
	s_nop 3
	v_mul_f32_e32 v36, 0x3e38aa3b, v36
	v_mul_f32_e32 v37, 0x3e38aa3b, v37
	v_exp_f32_e64 v96, -|v36|
	v_exp_f32_e64 v97, -|v37|
	v_min_f32_e64 v104, -v36, 0
	v_min_f32_e64 v105, -v37, 0
	v_add_f32_e32 v96, 1.0, v96
	v_add_f32_e32 v97, 1.0, v97
	v_log_f32_e32 v96, v96
	v_log_f32_e32 v97, v97
	v_cndmask_b32_e64 v121, v102, 0, s[12:13]
	v_sub_f32_e32 v104, v104, v96
	v_sub_f32_e32 v105, v105, v97
	v_mul_f32_e32 v38, 0x3e38aa3b, v38
	v_mul_f32_e32 v39, 0x3e38aa3b, v39
	v_exp_f32_e64 v103, -|v38|
	v_exp_f32_e64 v120, -|v39|
	v_min_f32_e64 v106, -v38, 0
	v_min_f32_e64 v107, -v39, 0
	v_add_f32_e32 v103, 1.0, v103
	v_add_f32_e32 v120, 1.0, v120
	v_log_f32_e32 v103, v103
	v_log_f32_e32 v120, v120
	v_sub_f32_e32 v106, v106, v103
	v_sub_f32_e32 v107, v107, v120
	v_mul_f32_e32 v40, 0x3e38aa3b, v40
	v_mul_f32_e32 v41, 0x3e38aa3b, v41
	v_exp_f32_e64 v96, -|v40|
	v_exp_f32_e64 v97, -|v41|
	v_min_f32_e64 v108, -v40, 0
	v_min_f32_e64 v109, -v41, 0
	v_add_f32_e32 v96, 1.0, v96
	v_add_f32_e32 v97, 1.0, v97
	v_log_f32_e32 v96, v96
	v_log_f32_e32 v97, v97
	v_sub_f32_e32 v108, v108, v96
	v_sub_f32_e32 v109, v109, v97
	v_mul_f32_e32 v42, 0x3e38aa3b, v42
	v_mul_f32_e32 v43, 0x3e38aa3b, v43
	v_exp_f32_e64 v103, -|v42|
	v_exp_f32_e64 v120, -|v43|
	v_min_f32_e64 v110, -v42, 0
	v_min_f32_e64 v111, -v43, 0
	v_add_f32_e32 v103, 1.0, v103
	v_add_f32_e32 v120, 1.0, v120
	v_log_f32_e32 v103, v103
	v_log_f32_e32 v120, v120
	v_sub_f32_e32 v110, v110, v103
	v_sub_f32_e32 v111, v111, v120
	v_mul_f32_e32 v44, 0x3e38aa3b, v44
	v_mul_f32_e32 v45, 0x3e38aa3b, v45
	v_exp_f32_e64 v96, -|v44|
	v_exp_f32_e64 v97, -|v45|
	v_min_f32_e64 v112, -v44, 0
	v_min_f32_e64 v113, -v45, 0
	v_add_f32_e32 v96, 1.0, v96
	v_add_f32_e32 v97, 1.0, v97
	v_log_f32_e32 v96, v96
	v_log_f32_e32 v97, v97
	v_sub_f32_e32 v112, v112, v96
	v_sub_f32_e32 v113, v113, v97
	v_mul_f32_e32 v46, 0x3e38aa3b, v46
	v_mul_f32_e32 v47, 0x3e38aa3b, v47
	v_exp_f32_e64 v103, -|v46|
	v_exp_f32_e64 v120, -|v47|
	v_min_f32_e64 v114, -v46, 0
	v_min_f32_e64 v115, -v47, 0
	v_add_f32_e32 v103, 1.0, v103
	v_add_f32_e32 v120, 1.0, v120
	v_log_f32_e32 v103, v103
	v_log_f32_e32 v120, v120
	v_sub_f32_e32 v114, v114, v103
	v_sub_f32_e32 v115, v115, v120
	v_mul_f32_e32 v48, 0x3e38aa3b, v48
	v_mul_f32_e32 v49, 0x3e38aa3b, v49
	v_exp_f32_e64 v96, -|v48|
	v_exp_f32_e64 v97, -|v49|
	v_min_f32_e64 v116, -v48, 0
	v_min_f32_e64 v117, -v49, 0
	v_add_f32_e32 v96, 1.0, v96
	v_add_f32_e32 v97, 1.0, v97
	v_log_f32_e32 v96, v96
	v_log_f32_e32 v97, v97
	v_sub_f32_e32 v116, v116, v96
	v_sub_f32_e32 v117, v117, v97
	v_mul_f32_e32 v50, 0x3e38aa3b, v50
	v_mul_f32_e32 v51, 0x3e38aa3b, v51
	v_exp_f32_e64 v103, -|v50|
	v_exp_f32_e64 v120, -|v51|
	v_min_f32_e64 v118, -v50, 0
	v_min_f32_e64 v119, -v51, 0
	v_add_f32_e32 v103, 1.0, v103
	v_add_f32_e32 v120, 1.0, v120
	v_log_f32_e32 v103, v103
	v_log_f32_e32 v120, v120
	v_sub_f32_e32 v118, v118, v103
	v_sub_f32_e32 v119, v119, v120
	v_add_f32_e32 v106, v106, v107
	v_add_f32_e32 v110, v110, v111
	v_add_f32_e32 v114, v114, v115
	v_add_f32_e32 v118, v118, v119
	v_add_f32_e32 v105, v105, v106
	v_add_f32_e32 v109, v109, v110
	v_add_f32_e32 v113, v113, v114
	v_add_f32_e32 v117, v117, v118
	v_add_f32_e32 v104, v104, v105
	v_add_f32_e32 v108, v108, v109
	v_add_f32_e32 v112, v112, v113
	v_add_f32_e32 v116, v116, v117
	v_add_f32_e32 v122, v116, v121
	v_add_f32_e32 v36, v36, v104
	v_add_f32_e32 v37, v37, v105
	v_add_f32_e32 v38, v38, v106
	v_add_f32_e32 v39, v39, v107
	v_add_f32_e32 v123, v122, v112
	v_add_f32_e32 v40, v40, v108
	v_add_f32_e32 v41, v41, v109
	v_add_f32_e32 v42, v42, v110
	v_add_f32_e32 v43, v43, v111
	v_add_f32_e32 v124, v123, v108
	v_add_f32_e32 v44, v44, v112
	v_add_f32_e32 v45, v45, v113
	v_add_f32_e32 v46, v46, v114
	v_add_f32_e32 v47, v47, v115
	v_add_f32_e32 v125, v124, v104
	v_add_f32_e32 v48, v48, v116
	v_add_f32_e32 v49, v49, v117
	v_add_f32_e32 v50, v50, v118
	v_add_f32_e32 v51, v51, v119
	v_mov_b32_e32 v126, v122
	v_cndmask_b32_e64 v130, v121, v125, s[12:13]
	v_cndmask_b32_e64 v127, v123, v122, s[12:13]
	v_cndmask_b32_e64 v128, v124, v123, s[12:13]
	v_cndmask_b32_e64 v129, v125, v124, s[12:13]
	v_permlane32_swap_b32_e32 v126, v130
	v_permlane32_swap_b32_e32 v127, v122
	v_permlane32_swap_b32_e32 v128, v123
	v_permlane32_swap_b32_e32 v129, v124
	v_add_f32_e32 v102, v125, v126
	v_add_f32_e32 v127, v127, v122
	v_add_f32_e32 v128, v128, v123
	v_add_f32_e32 v129, v129, v124
	v_add_f32_e32 v48, v48, v130
	v_add_f32_e32 v49, v49, v130
	v_add_f32_e32 v50, v50, v130
	v_add_f32_e32 v51, v51, v130
	v_add_f32_e32 v44, v44, v127
	v_add_f32_e32 v45, v45, v127
	v_add_f32_e32 v46, v46, v127
	v_add_f32_e32 v47, v47, v127
	v_add_f32_e32 v40, v40, v128
	v_add_f32_e32 v41, v41, v128
	v_add_f32_e32 v42, v42, v128
	v_add_f32_e32 v43, v43, v128
	v_add_f32_e32 v36, v36, v129
	v_add_f32_e32 v37, v37, v129
	v_add_f32_e32 v38, v38, v129
	v_add_f32_e32 v39, v39, v129
	v_exp_f32_e64 v36, v36 clamp
	v_exp_f32_e64 v37, v37 clamp
	v_exp_f32_e64 v38, v38 clamp
	v_exp_f32_e64 v39, v39 clamp
	v_exp_f32_e64 v40, v40 clamp
	v_exp_f32_e64 v41, v41 clamp
	v_exp_f32_e64 v42, v42 clamp
	v_exp_f32_e64 v43, v43 clamp
	v_exp_f32_e64 v44, v44 clamp
	v_exp_f32_e64 v45, v45 clamp
	v_exp_f32_e64 v46, v46 clamp
	v_exp_f32_e64 v47, v47 clamp
	v_exp_f32_e64 v48, v48 clamp
	v_exp_f32_e64 v49, v49 clamp
	v_exp_f32_e64 v50, v50 clamp
	v_exp_f32_e64 v51, v51 clamp
	s_nop 0
	v_cvt_pk_bf16_f32 v36, v36, v37
	v_cvt_pk_bf16_f32 v37, v38, v39
	v_cvt_pk_bf16_f32 v38, v40, v41
	v_cvt_pk_bf16_f32 v39, v42, v43
	s_mov_b32 s4, 0xc3160a50
	v_cmp_gt_f32_e32 vcc, s4, v102
	v_mfma_f32_32x32x16_bf16 v[4:19], v[168:171], v[36:39], v[4:19]
	v_cvt_pk_bf16_f32 v44, v44, v45
	v_cvt_pk_bf16_f32 v45, v46, v47
	v_mfma_f32_32x32x16_bf16 v[20:35], v[164:167], v[36:39], v[20:35]
	v_cvt_pk_bf16_f32 v46, v48, v49
	v_cvt_pk_bf16_f32 v47, v50, v51
	s_cmp_eq_u32 vcc_hi, exec_hi
	s_cselect_b64 s[4:5], -1, 0
	v_cmp_eq_u32_e32 vcc, s28, v98
	s_or_b64 s[4:5], s[4:5], vcc
	s_add_i32 s28, s28, 1
	s_and_b64 s[4:5], exec, s[4:5]
	s_or_b64 s[34:35], s[4:5], s[34:35]
	v_mfma_f32_32x32x16_bf16 v[4:19], v[160:163], v[44:47], v[4:19]
	v_mfma_f32_32x32x16_bf16 v[20:35], v[156:159], v[44:47], v[20:35]
	s_andn2_b64 exec, exec, s[34:35]
	s_cbranch_execz .Lsbu_exit
; __device__ __forceinline__ void sb_load(SbFrags& F, const bf16_t* Pm, const bf16_t* VT, size_t tok0, int kv0, int h, int r32, int hi) {
;     const bf16_t* krow = Pm + (tok0 + kv0 + r32) * PW + PC_SBK + h * 64;
; #pragma unroll
;     for (int s = 0; s < 4; ++s) F.kf[s] = *(const bf16x8*)(krow + 16 * s + 8 * hi);
; #pragma unroll
;     for (int s = 0; s < 2; ++s) {
;         const bf16_t* v0p = VT + (size_t)(h * 64 + r32) * VTLD + tok0 + kv0 + 16 * s + 4 * hi; const bf16_t* v1p = v0p + (size_t)32 * VTLD;
;         F.v[4 * s + 0] = *(const s16x4*)v0p; F.v[4 * s + 1] = *(const s16x4*)(v0p + 8); F.v[4 * s + 2] = *(const s16x4*)v1p; F.v[4 * s + 3] = *(const s16x4*)(v1p + 8);
;     }
; }
; template <bool DRY> __device__ __forceinline__ void sb_unit(int b, int h, int qi, bf16_t* Pm, const bf16_t* VT) {
;     ...
;         sb_load(nxt, Pm, VT, tok0, (kt > 0 ? kt - 1 : 0) * 32, h, r32, hi);
	v_med3_i32 v36, v100, 0, 1
	v_lshlrev_b32_e32 v36, 5, v36
	s_mov_b32 s4, 0x208000
	v_sub_u32_e32 v40, v99, v36
	v_add_co_u32_e32 v36, vcc, s4, v94
	v_mov_b32_e32 v41, v2
	s_nop 0
	v_addc_co_u32_e32 v37, vcc, 0, v95, vcc
	global_load_dwordx4 v[156:159], v[36:37], off offset:32
	global_load_dwordx4 v[160:163], v[94:95], off offset:32
	global_load_dwordx4 v[164:167], v[36:37], off
	global_load_dwordx4 v[168:171], v[94:95], off
	v_mad_u64_u32 v[36:37], s[4:5], v90, s24, v[92:93]
	v_mov_b32_e32 v38, v37
	v_mad_u64_u32 v[38:39], s[4:5], v91, s24, v[38:39]
	v_mov_b32_e32 v37, v38
	global_load_dwordx4 v[152:155], v[36:37], off offset:2400
	global_load_dwordx4 v[148:151], v[36:37], off offset:2368
	global_load_dwordx4 v[144:147], v[36:37], off offset:2336
	s_nop 0
	global_load_dwordx4 v[140:143], v[36:37], off offset:2304
	v_lshl_add_u64 v[90:91], v[0:1], 0, v[40:41]
	v_lshl_add_u64 v[94:95], v[40:41], 1, v[88:89]
	v_add_u32_e32 v100, -1, v100
	v_subrev_u32_e32 v99, 32, v99
	s_waitcnt vmcnt(8)
; __device__ __forceinline__ int crow(int r, int hi) { return (r & 3) + 8 * (r >> 2) + 4 * hi; }
; template <bool DRY> __device__ __forceinline__ void sb_unit(int b, int h, int qi, bf16_t* Pm, const bf16_t* VT) {
;     ...
;         for (int s = 0; s < 4; ++s) p = __builtin_amdgcn_mfma_f32_32x32x16_bf16(cur.kf[s], qf[s], p, 0, 0, 0);
;         const bool diag = (kt == qi);
;         float lk[16], inner[16], Tg[4], TP[4], pre[4];
; #pragma unroll
;         for (int r = 0; r < 16; ++r) {
;             const float z = p[r] * 0.125f; p[r] = z;
;             const float e = __expf(-fabsf(z)); const float sp = fmaxf(z, 0.f) + __logf(1.f + e);
;             const bool valid = !diag || (crow(r, hi) < r32);
;             lk[r] = valid ? -sp : 0.f;
;         }
; #pragma unroll
;         for (int g = 0; g < 4; ++g) {
;             const float s3 = lk[4 * g + 3], s2 = s3 + lk[4 * g + 2], s1 = s2 + lk[4 * g + 1];
;             inner[4 * g + 3] = 0.f; inner[4 * g + 2] = s3; inner[4 * g + 1] = s2; inner[4 * g] = s1; Tg[g] = s1 + lk[4 * g];
;             TP[g] = __shfl_xor(Tg[g], 32);
;         }
;         float run = 0.f;
; #pragma unroll
;         for (int g = 3; g >= 0; --g) { pre[g] = run + (hi == 0 ? TP[g] : 0.f); run += Tg[g] + TP[g]; }
; #pragma unroll
;         for (int r = 0; r < 16; ++r) {
;             const bool valid = !diag || (crow(r, hi) < r32);
;             const float ex = fminf(p[r] + lk[r] + R + pre[r >> 2] + inner[r], 0.f);
;             p[r] = valid ? __expf(ex) : 0.f;
;         }
;         R += run;
; #pragma unroll
;         for (int s = 0; s < 2; ++s) {
;             const u32x4 pw = (u32x4){cvtpk(p[8 * s + 0], p[8 * s + 1]), cvtpk(p[8 * s + 2], p[8 * s + 3]), cvtpk(p[8 * s + 4], p[8 * s + 5]), cvtpk(p[8 * s + 6], p[8 * s + 7])};
;             const bf16x8 pf = __builtin_bit_cast(bf16x8, pw);
;             const s16x4 l0 = cur.v[4 * s], h0 = cur.v[4 * s + 1], l1 = cur.v[4 * s + 2], h1 = cur.v[4 * s + 3];
;             const bf16x8 v0 = (bf16x8){l0[0], l0[1], l0[2], l0[3], h0[0], h0[1], h0[2], h0[3]};
;             const bf16x8 v1 = (bf16x8){l1[0], l1[1], l1[2], l1[3], h1[0], h1[1], h1[2], h1[3]};
;             o0 = __builtin_amdgcn_mfma_f32_32x32x16_bf16(v0, pf, o0, 0, 0, 0);
;             o1 = __builtin_amdgcn_mfma_f32_32x32x16_bf16(v1, pf, o1, 0, 0, 0);
;         }
;         if (__all(R < -104.f)) break;
;         cur = nxt;
;     }
	v_mfma_f32_32x32x16_bf16 v[36:51], v[172:175], v[52:55], 0
	v_mfma_f32_32x32x16_bf16 v[36:51], v[176:179], v[56:59], v[36:51]
	v_mfma_f32_32x32x16_bf16 v[36:51], v[180:183], v[60:63], v[36:51]
	v_mfma_f32_32x32x16_bf16 v[36:51], v[184:187], v[64:67], v[36:51]
	v_permlane32_swap_b32_e32 v80, v82
	v_permlane32_swap_b32_e32 v81, v83
	v_permlane32_swap_b32_e32 v72, v74
	v_permlane32_swap_b32_e32 v73, v75
	v_permlane32_swap_b32_e32 v76, v78
	v_permlane32_swap_b32_e32 v77, v79
	v_permlane32_swap_b32_e32 v68, v70
	v_permlane32_swap_b32_e32 v69, v71
	s_nop 3
	v_mul_f32_e32 v36, 0x3e38aa3b, v36
	v_mul_f32_e32 v37, 0x3e38aa3b, v37
	v_exp_f32_e64 v96, -|v36|
	v_exp_f32_e64 v97, -|v37|
	v_min_f32_e64 v104, -v36, 0
	v_min_f32_e64 v105, -v37, 0
	v_add_f32_e32 v96, 1.0, v96
	v_add_f32_e32 v97, 1.0, v97
	v_log_f32_e32 v96, v96
	v_log_f32_e32 v97, v97
	v_cndmask_b32_e64 v121, v102, 0, s[12:13]
	v_sub_f32_e32 v104, v104, v96
	v_sub_f32_e32 v105, v105, v97
	v_mul_f32_e32 v38, 0x3e38aa3b, v38
	v_mul_f32_e32 v39, 0x3e38aa3b, v39
	v_exp_f32_e64 v103, -|v38|
	v_exp_f32_e64 v120, -|v39|
	v_min_f32_e64 v106, -v38, 0
	v_min_f32_e64 v107, -v39, 0
	v_add_f32_e32 v103, 1.0, v103
	v_add_f32_e32 v120, 1.0, v120
	v_log_f32_e32 v103, v103
	v_log_f32_e32 v120, v120
	v_sub_f32_e32 v106, v106, v103
	v_sub_f32_e32 v107, v107, v120
	v_mul_f32_e32 v40, 0x3e38aa3b, v40
	v_mul_f32_e32 v41, 0x3e38aa3b, v41
	v_exp_f32_e64 v96, -|v40|
	v_exp_f32_e64 v97, -|v41|
	v_min_f32_e64 v108, -v40, 0
	v_min_f32_e64 v109, -v41, 0
	v_add_f32_e32 v96, 1.0, v96
	v_add_f32_e32 v97, 1.0, v97
	v_log_f32_e32 v96, v96
	v_log_f32_e32 v97, v97
	v_sub_f32_e32 v108, v108, v96
	v_sub_f32_e32 v109, v109, v97
	v_mul_f32_e32 v42, 0x3e38aa3b, v42
	v_mul_f32_e32 v43, 0x3e38aa3b, v43
	v_exp_f32_e64 v103, -|v42|
	v_exp_f32_e64 v120, -|v43|
	v_min_f32_e64 v110, -v42, 0
	v_min_f32_e64 v111, -v43, 0
	v_add_f32_e32 v103, 1.0, v103
	v_add_f32_e32 v120, 1.0, v120
	v_log_f32_e32 v103, v103
	v_log_f32_e32 v120, v120
	v_sub_f32_e32 v110, v110, v103
	v_sub_f32_e32 v111, v111, v120
	v_mul_f32_e32 v44, 0x3e38aa3b, v44
	v_mul_f32_e32 v45, 0x3e38aa3b, v45
	v_exp_f32_e64 v96, -|v44|
	v_exp_f32_e64 v97, -|v45|
	v_min_f32_e64 v112, -v44, 0
	v_min_f32_e64 v113, -v45, 0
	v_add_f32_e32 v96, 1.0, v96
	v_add_f32_e32 v97, 1.0, v97
	v_log_f32_e32 v96, v96
	v_log_f32_e32 v97, v97
	v_sub_f32_e32 v112, v112, v96
	v_sub_f32_e32 v113, v113, v97
	v_mul_f32_e32 v46, 0x3e38aa3b, v46
	v_mul_f32_e32 v47, 0x3e38aa3b, v47
	v_exp_f32_e64 v103, -|v46|
	v_exp_f32_e64 v120, -|v47|
	v_min_f32_e64 v114, -v46, 0
	v_min_f32_e64 v115, -v47, 0
	v_add_f32_e32 v103, 1.0, v103
	v_add_f32_e32 v120, 1.0, v120
	v_log_f32_e32 v103, v103
	v_log_f32_e32 v120, v120
	v_sub_f32_e32 v114, v114, v103
	v_sub_f32_e32 v115, v115, v120
	v_mul_f32_e32 v48, 0x3e38aa3b, v48
	v_mul_f32_e32 v49, 0x3e38aa3b, v49
	v_exp_f32_e64 v96, -|v48|
	v_exp_f32_e64 v97, -|v49|
	v_min_f32_e64 v116, -v48, 0
	v_min_f32_e64 v117, -v49, 0
	v_add_f32_e32 v96, 1.0, v96
	v_add_f32_e32 v97, 1.0, v97
	v_log_f32_e32 v96, v96
	v_log_f32_e32 v97, v97
	v_sub_f32_e32 v116, v116, v96
	v_sub_f32_e32 v117, v117, v97
	v_mul_f32_e32 v50, 0x3e38aa3b, v50
	v_mul_f32_e32 v51, 0x3e38aa3b, v51
	v_exp_f32_e64 v103, -|v50|
	v_exp_f32_e64 v120, -|v51|
	v_min_f32_e64 v118, -v50, 0
	v_min_f32_e64 v119, -v51, 0
	v_add_f32_e32 v103, 1.0, v103
	v_add_f32_e32 v120, 1.0, v120
	v_log_f32_e32 v103, v103
	v_log_f32_e32 v120, v120
	v_sub_f32_e32 v118, v118, v103
	v_sub_f32_e32 v119, v119, v120
	v_add_f32_e32 v106, v106, v107
	v_add_f32_e32 v110, v110, v111
	v_add_f32_e32 v114, v114, v115
	v_add_f32_e32 v118, v118, v119
	v_add_f32_e32 v105, v105, v106
	v_add_f32_e32 v109, v109, v110
	v_add_f32_e32 v113, v113, v114
	v_add_f32_e32 v117, v117, v118
	v_add_f32_e32 v104, v104, v105
	v_add_f32_e32 v108, v108, v109
	v_add_f32_e32 v112, v112, v113
	v_add_f32_e32 v116, v116, v117
	v_add_f32_e32 v122, v116, v121
	v_add_f32_e32 v36, v36, v104
	v_add_f32_e32 v37, v37, v105
	v_add_f32_e32 v38, v38, v106
	v_add_f32_e32 v39, v39, v107
	v_add_f32_e32 v123, v122, v112
	v_add_f32_e32 v40, v40, v108
	v_add_f32_e32 v41, v41, v109
	v_add_f32_e32 v42, v42, v110
	v_add_f32_e32 v43, v43, v111
	v_add_f32_e32 v124, v123, v108
	v_add_f32_e32 v44, v44, v112
	v_add_f32_e32 v45, v45, v113
	v_add_f32_e32 v46, v46, v114
	v_add_f32_e32 v47, v47, v115
	v_add_f32_e32 v125, v124, v104
	v_add_f32_e32 v48, v48, v116
	v_add_f32_e32 v49, v49, v117
	v_add_f32_e32 v50, v50, v118
	v_add_f32_e32 v51, v51, v119
	v_mov_b32_e32 v126, v122
	v_cndmask_b32_e64 v130, v121, v125, s[12:13]
	v_cndmask_b32_e64 v127, v123, v122, s[12:13]
	v_cndmask_b32_e64 v128, v124, v123, s[12:13]
	v_cndmask_b32_e64 v129, v125, v124, s[12:13]
	v_permlane32_swap_b32_e32 v126, v130
	v_permlane32_swap_b32_e32 v127, v122
	v_permlane32_swap_b32_e32 v128, v123
	v_permlane32_swap_b32_e32 v129, v124
	v_add_f32_e32 v102, v125, v126
	v_add_f32_e32 v127, v127, v122
	v_add_f32_e32 v128, v128, v123
	v_add_f32_e32 v129, v129, v124
	v_add_f32_e32 v48, v48, v130
	v_add_f32_e32 v49, v49, v130
	v_add_f32_e32 v50, v50, v130
	v_add_f32_e32 v51, v51, v130
	v_add_f32_e32 v44, v44, v127
	v_add_f32_e32 v45, v45, v127
	v_add_f32_e32 v46, v46, v127
	v_add_f32_e32 v47, v47, v127
	v_add_f32_e32 v40, v40, v128
	v_add_f32_e32 v41, v41, v128
	v_add_f32_e32 v42, v42, v128
	v_add_f32_e32 v43, v43, v128
	v_add_f32_e32 v36, v36, v129
	v_add_f32_e32 v37, v37, v129
	v_add_f32_e32 v38, v38, v129
	v_add_f32_e32 v39, v39, v129
	v_exp_f32_e64 v36, v36 clamp
	v_exp_f32_e64 v37, v37 clamp
	v_exp_f32_e64 v38, v38 clamp
	v_exp_f32_e64 v39, v39 clamp
	v_exp_f32_e64 v40, v40 clamp
	v_exp_f32_e64 v41, v41 clamp
	v_exp_f32_e64 v42, v42 clamp
	v_exp_f32_e64 v43, v43 clamp
	v_exp_f32_e64 v44, v44 clamp
	v_exp_f32_e64 v45, v45 clamp
	v_exp_f32_e64 v46, v46 clamp
	v_exp_f32_e64 v47, v47 clamp
	v_exp_f32_e64 v48, v48 clamp
	v_exp_f32_e64 v49, v49 clamp
	v_exp_f32_e64 v50, v50 clamp
	v_exp_f32_e64 v51, v51 clamp
	s_nop 0
	v_cvt_pk_bf16_f32 v36, v36, v37
	v_cvt_pk_bf16_f32 v37, v38, v39
	v_cvt_pk_bf16_f32 v38, v40, v41
	v_cvt_pk_bf16_f32 v39, v42, v43
	s_mov_b32 s4, 0xc3160a50
	v_cmp_gt_f32_e32 vcc, s4, v102
	v_mfma_f32_32x32x16_bf16 v[4:19], v[80:83], v[36:39], v[4:19]
	v_cvt_pk_bf16_f32 v44, v44, v45
	v_cvt_pk_bf16_f32 v45, v46, v47
	v_mfma_f32_32x32x16_bf16 v[20:35], v[76:79], v[36:39], v[20:35]
	v_cvt_pk_bf16_f32 v46, v48, v49
	v_cvt_pk_bf16_f32 v47, v50, v51
	s_cmp_eq_u32 vcc_hi, exec_hi
	s_cselect_b64 s[4:5], -1, 0
	v_cmp_eq_u32_e32 vcc, s28, v98
	s_or_b64 s[4:5], s[4:5], vcc
	s_add_i32 s28, s28, 1
	s_and_b64 s[4:5], exec, s[4:5]
	s_or_b64 s[34:35], s[4:5], s[34:35]
	v_mfma_f32_32x32x16_bf16 v[4:19], v[72:75], v[44:47], v[4:19]
	v_mfma_f32_32x32x16_bf16 v[20:35], v[68:71], v[44:47], v[20:35]
	s_andn2_b64 exec, exec, s[34:35]
	s_cbranch_execnz .Lsbu_loop
